# MoBA/FoX: fused kk=1 and kk=0 sub-tiles run back to back; kk=0 K fragments read from LDS under kk=1 softmax, V fragments under kk=0 QK
# speedup vs baseline: 1.0051x; 1.0051x over previous
; #define LAS __attribute__((address_space(3)))
; DI float ex2(float x) { return __builtin_amdgcn_exp2f(x); }
; template <int MODE>
; DI void sub_tile(const bf16x8 (&kf)[4], const bf16x8 (&vf)[2][2], const bf16x8 (&qf)[4], f32x16& o0, f32x16& o1, float& l, bool diag, float offs, float fm, const LAS float* fsp, int r, int h) {
;     ...
;         x = qk_tile(kf, qf);
; #pragma unroll
;         for (int g = 0; g < 4; ++g) {
;             const f32x4 fs = *(const LAS f32x4*)(fsp + 16 * (g >> 1) + 8 * h + 4 * (g & 1));
; #pragma unroll
;             for (int e = 0; e < 4; ++e) p[4 * g + e] = ex2(x[4 * g + e] + (fm - fs[e]));
;         }
;     }
;     if (diag) {
; #pragma unroll
;         for (int i = 0; i < 16; ++i) if (kidx(i, h) > r) p[i] = 0.f;
;     }
; #pragma unroll
;     for (int i = 0; i < 16; ++i) l += p[i];
;     pv_tile(o0, o1, vf, p);
; template <int MODE>
; DI void attn_wg2_item(const bf16_t* Qm, const bf16_t* Km, const bf16_t* Vtm, const float* Fb, const float* KMPb, const bf16_t* G, bf16_t* Y, int bh, int qb2, int halfq, int mixer, float Mb, LAS unsigned char* lds, int tid, int wave, int lane) {
;     ...
;                 bf16x8 kf[4], vf[2][2];
; #pragma unroll
;                 for (int sp = 0; sp < 4; ++sp) kf[sp] = *(LAS bf16x8*)(lb + kra + kk * 32 * 144 + sp * 32);
; #pragma unroll
;                 for (int dd = 0; dd < 2; ++dd)
; #pragma unroll
;                     for (int s = 0; s < 2; ++s) vf[dd][s] = *(LAS bf16x8*)(lb + vra + dd * 32 * 144 + kk * 64 + s * 32);
;                 float offA = mb2, offB = mb2;
;                 if (MODE == 2) { offA = ((nb == qblkA) || ((selA >> nb) & 1u)) ? mb2 : NEGI; offB = ((nb == qblkB) || ((selB >> nb) & 1u)) ? mb2 : NEGI; }
;                 const LAS float* fsp = (const LAS float*)(lb + AW_F) + kk * 32;
;                 if (actA) sub_tile<MODE>(kf, vf, qfA, oA0, oA1, lA, tau == qtA, offA, fmA, fsp, r, h);
;                 if (actB) sub_tile<MODE>(kf, vf, qfB, oB0, oB1, lB, tau == qtB, offB, fmB, fsp, r, h);
.LBB0_331:
	s_mul_i32 s5, s85, 0x4900
	s_add_i32 s50, s5, 0
	s_lshl_b32 s5, s64, 1
	s_cmp_lt_i32 s5, s69
	s_cselect_b64 s[66:67], -1, 0
	s_cmp_lt_i32 s5, s84
	s_cselect_b64 s[64:65], -1, 0
	v_add_u32_e32 v0, s50, v192
	v_add_u32_e32 v15, s50, v196
	s_or_b64 s[78:79], s[66:67], s[64:65]
	s_andn2_b64 vcc, exec, s[78:79]
	v_add_u32_e32 v14, v0, v194
	v_add_u32_e32 v0, v15, v194
	s_cbranch_vccnz .LBB0_340
	ds_read_b128 v[144:147], v14 offset:4608
	ds_read_b128 v[148:151], v14 offset:4640
	ds_read_b128 v[152:155], v14 offset:4672
	ds_read_b128 v[156:159], v14 offset:4704
	ds_read_b128 v[140:143], v0 offset:9280
	ds_read_b128 v[136:139], v0 offset:9312
	ds_read_b128 v[132:135], v0 offset:13888
	ds_read_b128 v[128:131], v0 offset:13920
	s_and_b64 s[78:79], s[66:67], s[64:65]
	s_cbranch_scc0 .Lfox_nf1
	s_or_b32 s78, s5, 1
	s_cmp_eq_u32 s78, s69
	s_cbranch_scc1 .Lfox_nf1
	s_cmp_eq_u32 s78, s84
	s_cbranch_scc1 .Lfox_nf1
	v_add_u32_e32 v179, s50, v197
	ds_read_b128 v[200:203], v179 offset:18560
	ds_read_b128 v[204:207], v179 offset:18576
	ds_read_b128 v[208:211], v179 offset:18624
	ds_read_b128 v[212:215], v179 offset:18640
	s_waitcnt lgkmcnt(0)
	v_sub_f32_e32 v80, v188, v200
	v_sub_f32_e32 v81, v188, v201
	v_sub_f32_e32 v82, v188, v202
	v_sub_f32_e32 v83, v188, v203
	v_sub_f32_e32 v84, v188, v204
	v_sub_f32_e32 v85, v188, v205
	v_sub_f32_e32 v86, v188, v206
	v_sub_f32_e32 v87, v188, v207
	v_sub_f32_e32 v88, v188, v208
	v_sub_f32_e32 v89, v188, v209
	v_sub_f32_e32 v90, v188, v210
	v_sub_f32_e32 v91, v188, v211
	v_sub_f32_e32 v92, v188, v212
	v_sub_f32_e32 v93, v188, v213
	v_sub_f32_e32 v94, v188, v214
	v_sub_f32_e32 v95, v188, v215
	s_nop 1
	v_mfma_f32_32x32x16_bf16 v[80:95], v[144:147], v[96:99], v[80:95]
	v_mfma_f32_32x32x16_bf16 v[80:95], v[148:151], v[100:103], v[80:95]
	v_mfma_f32_32x32x16_bf16 v[80:95], v[152:155], v[104:107], v[80:95]
	v_mfma_f32_32x32x16_bf16 v[80:95], v[156:159], v[108:111], v[80:95]
	v_sub_f32_e32 v220, v190, v200
	v_sub_f32_e32 v221, v190, v201
	v_sub_f32_e32 v222, v190, v202
	v_sub_f32_e32 v223, v190, v203
	v_sub_f32_e32 v224, v190, v204
	v_sub_f32_e32 v225, v190, v205
	v_sub_f32_e32 v226, v190, v206
	v_sub_f32_e32 v227, v190, v207
	v_sub_f32_e32 v228, v190, v208
	v_sub_f32_e32 v229, v190, v209
	v_sub_f32_e32 v230, v190, v210
	v_sub_f32_e32 v231, v190, v211
	v_sub_f32_e32 v232, v190, v212
	v_sub_f32_e32 v233, v190, v213
	v_sub_f32_e32 v234, v190, v214
	v_sub_f32_e32 v235, v190, v215
	s_nop 1
	v_mfma_f32_32x32x16_bf16 v[220:235], v[144:147], v[112:115], v[220:235]
	v_mfma_f32_32x32x16_bf16 v[220:235], v[148:151], v[116:119], v[220:235]
	v_mfma_f32_32x32x16_bf16 v[220:235], v[152:155], v[120:123], v[220:235]
	v_mfma_f32_32x32x16_bf16 v[220:235], v[156:159], v[124:127], v[220:235]
	v_exp_f32_e32 v80, v80
	v_exp_f32_e32 v81, v81
	v_exp_f32_e32 v82, v82
	v_exp_f32_e32 v83, v83
	v_exp_f32_e32 v84, v84
	v_exp_f32_e32 v85, v85
	v_exp_f32_e32 v86, v86
	v_exp_f32_e32 v87, v87
	v_exp_f32_e32 v88, v88
	v_exp_f32_e32 v89, v89
	v_exp_f32_e32 v90, v90
	v_exp_f32_e32 v91, v91
	v_exp_f32_e32 v92, v92
	v_exp_f32_e32 v93, v93
	v_exp_f32_e32 v94, v94
	v_exp_f32_e32 v95, v95
	ds_read_b128 v[144:147], v14
	ds_read_b128 v[148:151], v14 offset:32
	ds_read_b128 v[152:155], v14 offset:64
	ds_read_b128 v[156:159], v14 offset:96
	ds_read_b128 v[200:203], v179 offset:18432
	ds_read_b128 v[204:207], v179 offset:18448
	ds_read_b128 v[208:211], v179 offset:18496
	ds_read_b128 v[212:215], v179 offset:18512
	v_exp_f32_e32 v220, v220
	v_add_f32_e32 v198, v80, v198
	v_exp_f32_e32 v221, v221
	v_add_f32_e32 v198, v81, v198
	v_exp_f32_e32 v222, v222
	v_add_f32_e32 v198, v82, v198
	v_exp_f32_e32 v223, v223
	v_add_f32_e32 v198, v83, v198
	v_exp_f32_e32 v224, v224
	v_add_f32_e32 v198, v84, v198
	v_exp_f32_e32 v225, v225
	v_add_f32_e32 v198, v85, v198
	v_exp_f32_e32 v226, v226
	v_add_f32_e32 v198, v86, v198
	v_exp_f32_e32 v227, v227
	v_add_f32_e32 v198, v87, v198
	v_exp_f32_e32 v228, v228
	v_add_f32_e32 v198, v88, v198
	v_exp_f32_e32 v229, v229
	v_add_f32_e32 v198, v89, v198
	v_exp_f32_e32 v230, v230
	v_add_f32_e32 v198, v90, v198
	v_exp_f32_e32 v231, v231
	v_add_f32_e32 v198, v91, v198
	v_exp_f32_e32 v232, v232
	v_add_f32_e32 v198, v92, v198
	v_exp_f32_e32 v233, v233
	v_add_f32_e32 v198, v93, v198
	v_exp_f32_e32 v234, v234
	v_add_f32_e32 v198, v94, v198
	v_exp_f32_e32 v235, v235
	v_add_f32_e32 v198, v95, v198
	s_waitcnt lgkmcnt(0)
	v_cvt_pk_bf16_f32 v80, v80, v81
	v_cvt_pk_bf16_f32 v81, v82, v83
	v_cvt_pk_bf16_f32 v82, v84, v85
	v_cvt_pk_bf16_f32 v83, v86, v87
	v_cvt_pk_bf16_f32 v84, v88, v89
	v_cvt_pk_bf16_f32 v85, v90, v91
	v_cvt_pk_bf16_f32 v86, v92, v93
	v_cvt_pk_bf16_f32 v87, v94, v95
	v_mfma_f32_32x32x16_bf16 v[64:79], v[140:143], v[80:83], v[64:79]
	v_add_f32_e32 v175, v220, v175
	v_add_f32_e32 v175, v221, v175
	v_add_f32_e32 v175, v222, v175
	v_add_f32_e32 v175, v223, v175
	v_mfma_f32_32x32x16_bf16 v[48:63], v[132:135], v[80:83], v[48:63]
	v_add_f32_e32 v175, v224, v175
	v_add_f32_e32 v175, v225, v175
	v_add_f32_e32 v175, v226, v175
	v_add_f32_e32 v175, v227, v175
	v_mfma_f32_32x32x16_bf16 v[64:79], v[136:139], v[84:87], v[64:79]
	v_add_f32_e32 v175, v228, v175
	v_add_f32_e32 v175, v229, v175
	v_add_f32_e32 v175, v230, v175
	v_add_f32_e32 v175, v231, v175
	v_mfma_f32_32x32x16_bf16 v[48:63], v[128:131], v[84:87], v[48:63]
	v_add_f32_e32 v175, v232, v175
	v_add_f32_e32 v175, v233, v175
	v_add_f32_e32 v175, v234, v175
	v_add_f32_e32 v175, v235, v175
	v_cvt_pk_bf16_f32 v220, v220, v221
	v_cvt_pk_bf16_f32 v221, v222, v223
	v_cvt_pk_bf16_f32 v222, v224, v225
	v_cvt_pk_bf16_f32 v223, v226, v227
	v_cvt_pk_bf16_f32 v224, v228, v229
	v_cvt_pk_bf16_f32 v225, v230, v231
	v_cvt_pk_bf16_f32 v226, v232, v233
	v_cvt_pk_bf16_f32 v227, v234, v235
	v_mfma_f32_32x32x16_bf16 v[32:47], v[140:143], v[220:223], v[32:47]
	v_mfma_f32_32x32x16_bf16 v[16:31], v[132:135], v[220:223], v[16:31]
	v_mfma_f32_32x32x16_bf16 v[32:47], v[136:139], v[224:227], v[32:47]
	v_mfma_f32_32x32x16_bf16 v[16:31], v[128:131], v[224:227], v[16:31]
	s_waitcnt lgkmcnt(0)
; #define LAS __attribute__((address_space(3)))
; DI float ex2(float x) { return __builtin_amdgcn_exp2f(x); }
; template <int MODE>
; DI void sub_tile(const bf16x8 (&kf)[4], const bf16x8 (&vf)[2][2], const bf16x8 (&qf)[4], f32x16& o0, f32x16& o1, float& l, bool diag, float offs, float fm, const LAS float* fsp, int r, int h) {
;     ...
;         x = qk_tile(kf, qf);
; #pragma unroll
;         for (int g = 0; g < 4; ++g) {
;             const f32x4 fs = *(const LAS f32x4*)(fsp + 16 * (g >> 1) + 8 * h + 4 * (g & 1));
; #pragma unroll
;             for (int e = 0; e < 4; ++e) p[4 * g + e] = ex2(x[4 * g + e] + (fm - fs[e]));
;         }
;     }
;     if (diag) {
; #pragma unroll
;         for (int i = 0; i < 16; ++i) if (kidx(i, h) > r) p[i] = 0.f;
;     }
; #pragma unroll
;     for (int i = 0; i < 16; ++i) l += p[i];
;     pv_tile(o0, o1, vf, p);
; template <int MODE>
; DI void attn_wg2_item(const bf16_t* Qm, const bf16_t* Km, const bf16_t* Vtm, const float* Fb, const float* KMPb, const bf16_t* G, bf16_t* Y, int bh, int qb2, int halfq, int mixer, float Mb, LAS unsigned char* lds, int tid, int wave, int lane) {
;     ...
;                 bf16x8 kf[4], vf[2][2];
; #pragma unroll
;                 for (int sp = 0; sp < 4; ++sp) kf[sp] = *(LAS bf16x8*)(lb + kra + kk * 32 * 144 + sp * 32);
; #pragma unroll
;                 for (int dd = 0; dd < 2; ++dd)
; #pragma unroll
;                     for (int s = 0; s < 2; ++s) vf[dd][s] = *(LAS bf16x8*)(lb + vra + dd * 32 * 144 + kk * 64 + s * 32);
;                 float offA = mb2, offB = mb2;
;                 if (MODE == 2) { offA = ((nb == qblkA) || ((selA >> nb) & 1u)) ? mb2 : NEGI; offB = ((nb == qblkB) || ((selB >> nb) & 1u)) ? mb2 : NEGI; }
;                 const LAS float* fsp = (const LAS float*)(lb + AW_F) + kk * 32;
;                 if (actA) sub_tile<MODE>(kf, vf, qfA, oA0, oA1, lA, tau == qtA, offA, fmA, fsp, r, h);
;                 if (actB) sub_tile<MODE>(kf, vf, qfB, oB0, oB1, lB, tau == qtB, offB, fmB, fsp, r, h);
	v_sub_f32_e32 v80, v188, v200
	v_sub_f32_e32 v81, v188, v201
	v_sub_f32_e32 v82, v188, v202
	v_sub_f32_e32 v83, v188, v203
	v_sub_f32_e32 v84, v188, v204
	v_sub_f32_e32 v85, v188, v205
	v_sub_f32_e32 v86, v188, v206
	v_sub_f32_e32 v87, v188, v207
	v_sub_f32_e32 v88, v188, v208
	v_sub_f32_e32 v89, v188, v209
	v_sub_f32_e32 v90, v188, v210
	v_sub_f32_e32 v91, v188, v211
	v_sub_f32_e32 v92, v188, v212
	v_sub_f32_e32 v93, v188, v213
	v_sub_f32_e32 v94, v188, v214
	v_sub_f32_e32 v95, v188, v215
	s_nop 1
	v_mfma_f32_32x32x16_bf16 v[80:95], v[144:147], v[96:99], v[80:95]
	v_mfma_f32_32x32x16_bf16 v[80:95], v[148:151], v[100:103], v[80:95]
	v_mfma_f32_32x32x16_bf16 v[80:95], v[152:155], v[104:107], v[80:95]
	v_mfma_f32_32x32x16_bf16 v[80:95], v[156:159], v[108:111], v[80:95]
	ds_read_b128 v[140:143], v0 offset:9216
	ds_read_b128 v[136:139], v0 offset:9248
	ds_read_b128 v[132:135], v0 offset:13824
	ds_read_b128 v[128:131], v0 offset:13856
	v_sub_f32_e32 v220, v190, v200
	v_sub_f32_e32 v221, v190, v201
	v_sub_f32_e32 v222, v190, v202
	v_sub_f32_e32 v223, v190, v203
	v_sub_f32_e32 v224, v190, v204
	v_sub_f32_e32 v225, v190, v205
	v_sub_f32_e32 v226, v190, v206
	v_sub_f32_e32 v227, v190, v207
	v_sub_f32_e32 v228, v190, v208
	v_sub_f32_e32 v229, v190, v209
	v_sub_f32_e32 v230, v190, v210
	v_sub_f32_e32 v231, v190, v211
	v_sub_f32_e32 v232, v190, v212
	v_sub_f32_e32 v233, v190, v213
	v_sub_f32_e32 v234, v190, v214
	v_sub_f32_e32 v235, v190, v215
	s_nop 1
	v_mfma_f32_32x32x16_bf16 v[220:235], v[144:147], v[112:115], v[220:235]
	v_mfma_f32_32x32x16_bf16 v[220:235], v[148:151], v[116:119], v[220:235]
	v_mfma_f32_32x32x16_bf16 v[220:235], v[152:155], v[120:123], v[220:235]
	v_mfma_f32_32x32x16_bf16 v[220:235], v[156:159], v[124:127], v[220:235]
	v_exp_f32_e32 v80, v80
	v_exp_f32_e32 v81, v81
	v_exp_f32_e32 v82, v82
	v_exp_f32_e32 v83, v83
	v_exp_f32_e32 v84, v84
	v_exp_f32_e32 v85, v85
	v_exp_f32_e32 v86, v86
	v_exp_f32_e32 v87, v87
	v_exp_f32_e32 v88, v88
	v_exp_f32_e32 v89, v89
	v_exp_f32_e32 v90, v90
	v_exp_f32_e32 v91, v91
	v_exp_f32_e32 v92, v92
	v_exp_f32_e32 v93, v93
	v_exp_f32_e32 v94, v94
	v_exp_f32_e32 v95, v95
	v_exp_f32_e32 v220, v220
	v_add_f32_e32 v198, v80, v198
	v_exp_f32_e32 v221, v221
	v_add_f32_e32 v198, v81, v198
	v_exp_f32_e32 v222, v222
	v_add_f32_e32 v198, v82, v198
	v_exp_f32_e32 v223, v223
	v_add_f32_e32 v198, v83, v198
	v_exp_f32_e32 v224, v224
	v_add_f32_e32 v198, v84, v198
	v_exp_f32_e32 v225, v225
	v_add_f32_e32 v198, v85, v198
	v_exp_f32_e32 v226, v226
	v_add_f32_e32 v198, v86, v198
	v_exp_f32_e32 v227, v227
	v_add_f32_e32 v198, v87, v198
	v_exp_f32_e32 v228, v228
	v_add_f32_e32 v198, v88, v198
	v_exp_f32_e32 v229, v229
	v_add_f32_e32 v198, v89, v198
	v_exp_f32_e32 v230, v230
	v_add_f32_e32 v198, v90, v198
	v_exp_f32_e32 v231, v231
	v_add_f32_e32 v198, v91, v198
	v_exp_f32_e32 v232, v232
	v_add_f32_e32 v198, v92, v198
	v_exp_f32_e32 v233, v233
	v_add_f32_e32 v198, v93, v198
	v_exp_f32_e32 v234, v234
	v_add_f32_e32 v198, v94, v198
	v_exp_f32_e32 v235, v235
	v_add_f32_e32 v198, v95, v198
	s_waitcnt lgkmcnt(0)
	v_cvt_pk_bf16_f32 v80, v80, v81
	v_cvt_pk_bf16_f32 v81, v82, v83
	v_cvt_pk_bf16_f32 v82, v84, v85
	v_cvt_pk_bf16_f32 v83, v86, v87
	v_cvt_pk_bf16_f32 v84, v88, v89
	v_cvt_pk_bf16_f32 v85, v90, v91
	v_cvt_pk_bf16_f32 v86, v92, v93
	v_cvt_pk_bf16_f32 v87, v94, v95
	v_mfma_f32_32x32x16_bf16 v[64:79], v[140:143], v[80:83], v[64:79]
	v_add_f32_e32 v175, v220, v175
	v_add_f32_e32 v175, v221, v175
	v_add_f32_e32 v175, v222, v175
	v_add_f32_e32 v175, v223, v175
	v_mfma_f32_32x32x16_bf16 v[48:63], v[132:135], v[80:83], v[48:63]
	v_add_f32_e32 v175, v224, v175
	v_add_f32_e32 v175, v225, v175
	v_add_f32_e32 v175, v226, v175
	v_add_f32_e32 v175, v227, v175
	v_mfma_f32_32x32x16_bf16 v[64:79], v[136:139], v[84:87], v[64:79]
	v_add_f32_e32 v175, v228, v175
	v_add_f32_e32 v175, v229, v175
	v_add_f32_e32 v175, v230, v175
	v_add_f32_e32 v175, v231, v175
	v_mfma_f32_32x32x16_bf16 v[48:63], v[128:131], v[84:87], v[48:63]
	v_add_f32_e32 v175, v232, v175
	v_add_f32_e32 v175, v233, v175
	v_add_f32_e32 v175, v234, v175
	v_add_f32_e32 v175, v235, v175
	v_cvt_pk_bf16_f32 v220, v220, v221
	v_cvt_pk_bf16_f32 v221, v222, v223
	v_cvt_pk_bf16_f32 v222, v224, v225
	v_cvt_pk_bf16_f32 v223, v226, v227
	v_cvt_pk_bf16_f32 v224, v228, v229
	v_cvt_pk_bf16_f32 v225, v230, v231
	v_cvt_pk_bf16_f32 v226, v232, v233
	v_cvt_pk_bf16_f32 v227, v234, v235
	v_mfma_f32_32x32x16_bf16 v[32:47], v[140:143], v[220:223], v[32:47]
	v_mfma_f32_32x32x16_bf16 v[16:31], v[132:135], v[220:223], v[16:31]
	v_mfma_f32_32x32x16_bf16 v[32:47], v[136:139], v[224:227], v[32:47]
	v_mfma_f32_32x32x16_bf16 v[16:31], v[128:131], v[224:227], v[16:31]
	s_branch .LBB0_349

; #define LAS __attribute__((address_space(3)))
; DI f32x16 mfma32(bf16x8 a, bf16x8 b, f32x16 c) { return __builtin_amdgcn_mfma_f32_32x32x16_bf16(a, b, c, 0, 0, 0); }
; DI float ex2(float x) { return __builtin_amdgcn_exp2f(x); }
; template <int MODE>
; DI void sub_tile(const bf16x8 (&kf)[4], const bf16x8 (&vf)[2][2], const bf16x8 (&qf)[4], f32x16& o0, f32x16& o1, float& l, bool diag, float offs, float fm, const LAS float* fsp, int r, int h) {
;     ...
;     if (MODE == 2) {
; #pragma unroll
;         for (int i = 0; i < 16; ++i) x[i] = offs;
; #pragma unroll
;         for (int sp = 0; sp < 4; ++sp) x = mfma32(kf[sp], qf[sp], x);
; #pragma unroll
;         for (int i = 0; i < 16; ++i) p[i] = ex2(x[i]);
; template <int MODE>
; DI void attn_wg2_item(const bf16_t* Qm, const bf16_t* Km, const bf16_t* Vtm, const float* Fb, const float* KMPb, const bf16_t* G, bf16_t* Y, int bh, int qb2, int halfq, int mixer, float Mb, LAS unsigned char* lds, int tid, int wave, int lane) {
;     ...
;                 bf16x8 kf[4], vf[2][2];
; #pragma unroll
;                 for (int sp = 0; sp < 4; ++sp) kf[sp] = *(LAS bf16x8*)(lb + kra + kk * 32 * 144 + sp * 32);
; #pragma unroll
;                 for (int dd = 0; dd < 2; ++dd)
; #pragma unroll
;                     for (int s = 0; s < 2; ++s) vf[dd][s] = *(LAS bf16x8*)(lb + vra + dd * 32 * 144 + kk * 64 + s * 32);
;                 float offA = mb2, offB = mb2;
;                 if (MODE == 2) { offA = ((nb == qblkA) || ((selA >> nb) & 1u)) ? mb2 : NEGI; offB = ((nb == qblkB) || ((selB >> nb) & 1u)) ? mb2 : NEGI; }
;                 const LAS float* fsp = (const LAS float*)(lb + AW_F) + kk * 32;
;                 if (actA) sub_tile<MODE>(kf, vf, qfA, oA0, oA1, lA, tau == qtA, offA, fmA, fsp, r, h);
;                 if (actB) sub_tile<MODE>(kf, vf, qfB, oB0, oB1, lB, tau == qtB, offB, fmB, fsp, r, h);
.LBB0_393:
	s_mul_i32 s47, s79, 0x4900
	s_add_i32 s47, s47, 0
	s_lshl_b32 s87, s46, 1
	s_lshr_b32 s88, s46, 2
	s_cmp_lt_i32 s87, s84
	v_add_u32_e32 v0, s47, v175
	v_add_u32_e32 v10, s47, v173
	s_cselect_b64 s[46:47], -1, 0
	s_cmp_lt_i32 s87, s85
	s_cselect_b64 s[64:65], -1, 0
	s_lshl_b32 s89, 1, s88
	v_and_b32_e32 v11, s89, v176
	v_cmp_ne_u32_e32 vcc, 0, v11
	v_and_b32_e32 v11, s89, v177
	s_and_b64 s[48:49], s[46:47], vcc
	v_cmp_ne_u32_e64 s[46:47], 0, v11
	s_and_b64 s[66:67], s[64:65], s[46:47]
	s_or_b64 s[68:69], s[48:49], s[66:67]
	v_add_u32_e32 v14, v0, v172
	v_add_u32_e32 v0, v10, v172
	s_and_saveexec_b64 s[64:65], s[68:69]
	s_cbranch_execz .LBB0_403
	ds_read_b128 v[152:155], v14 offset:4608
	ds_read_b128 v[148:151], v14 offset:4640
	ds_read_b128 v[144:147], v14 offset:4672
	ds_read_b128 v[140:143], v14 offset:4704
	ds_read_b128 v[136:139], v0 offset:9280
	ds_read_b128 v[132:135], v0 offset:9312
	ds_read_b128 v[128:131], v0 offset:13888
	ds_read_b128 v[10:13], v0 offset:13920
	s_or_b32 s90, s87, 1
	s_and_b64 s[92:93], s[48:49], s[66:67]
	s_cbranch_scc0 .Lmoba_nf1
	s_cmp_eq_u32 s90, s84
	s_cbranch_scc1 .Lmoba_nf1
	s_cmp_eq_u32 s90, s85
	s_cbranch_scc1 .Lmoba_nf1
	s_waitcnt lgkmcnt(4)
	v_mfma_f32_32x32x16_bf16 v[80:95], v[152:155], v[96:99], v[196:211]
	v_mfma_f32_32x32x16_bf16 v[80:95], v[148:151], v[100:103], v[80:95]
	v_mfma_f32_32x32x16_bf16 v[80:95], v[144:147], v[104:107], v[80:95]
	v_mfma_f32_32x32x16_bf16 v[80:95], v[140:143], v[108:111], v[80:95]
	v_mfma_f32_32x32x16_bf16 v[228:243], v[152:155], v[112:115], v[212:227]
	v_mfma_f32_32x32x16_bf16 v[228:243], v[148:151], v[116:119], v[228:243]
	v_mfma_f32_32x32x16_bf16 v[228:243], v[144:147], v[120:123], v[228:243]
	v_mfma_f32_32x32x16_bf16 v[228:243], v[140:143], v[124:127], v[228:243]
	s_nop 7
	v_exp_f32_e32 v80, v80
	v_exp_f32_e32 v81, v81
	v_exp_f32_e32 v82, v82
	v_exp_f32_e32 v83, v83
	v_exp_f32_e32 v84, v84
	v_exp_f32_e32 v85, v85
	v_exp_f32_e32 v86, v86
	v_exp_f32_e32 v87, v87
	v_exp_f32_e32 v88, v88
	v_exp_f32_e32 v89, v89
	v_exp_f32_e32 v90, v90
	v_exp_f32_e32 v91, v91
	v_exp_f32_e32 v92, v92
	v_exp_f32_e32 v93, v93
	v_exp_f32_e32 v94, v94
	v_exp_f32_e32 v95, v95
	ds_read_b128 v[152:155], v14
	ds_read_b128 v[148:151], v14 offset:32
	ds_read_b128 v[144:147], v14 offset:64
	ds_read_b128 v[140:143], v14 offset:96
	v_exp_f32_e32 v228, v228
	v_add_f32_e32 v186, v80, v186
	v_exp_f32_e32 v229, v229
	v_add_f32_e32 v186, v81, v186
	v_exp_f32_e32 v230, v230
	v_add_f32_e32 v186, v82, v186
	v_exp_f32_e32 v231, v231
	v_add_f32_e32 v186, v83, v186
	v_exp_f32_e32 v232, v232
	v_add_f32_e32 v186, v84, v186
	v_exp_f32_e32 v233, v233
	v_add_f32_e32 v186, v85, v186
	v_exp_f32_e32 v234, v234
	v_add_f32_e32 v186, v86, v186
	v_exp_f32_e32 v235, v235
	v_add_f32_e32 v186, v87, v186
	v_exp_f32_e32 v236, v236
	v_add_f32_e32 v186, v88, v186
	v_exp_f32_e32 v237, v237
	v_add_f32_e32 v186, v89, v186
	v_exp_f32_e32 v238, v238
	v_add_f32_e32 v186, v90, v186
	v_exp_f32_e32 v239, v239
	v_add_f32_e32 v186, v91, v186
	v_exp_f32_e32 v240, v240
	v_add_f32_e32 v186, v92, v186
	v_exp_f32_e32 v241, v241
	v_add_f32_e32 v186, v93, v186
	v_exp_f32_e32 v242, v242
	v_add_f32_e32 v186, v94, v186
	v_exp_f32_e32 v243, v243
	v_add_f32_e32 v186, v95, v186
	s_waitcnt lgkmcnt(0)
	v_cvt_pk_bf16_f32 v80, v80, v81
	v_cvt_pk_bf16_f32 v81, v82, v83
	v_cvt_pk_bf16_f32 v82, v84, v85
	v_cvt_pk_bf16_f32 v83, v86, v87
	v_cvt_pk_bf16_f32 v84, v88, v89
	v_cvt_pk_bf16_f32 v85, v90, v91
	v_cvt_pk_bf16_f32 v86, v92, v93
	v_cvt_pk_bf16_f32 v87, v94, v95
	v_mfma_f32_32x32x16_bf16 v[64:79], v[136:139], v[80:83], v[64:79]
	v_add_f32_e32 v170, v228, v170
	v_add_f32_e32 v170, v229, v170
	v_add_f32_e32 v170, v230, v170
	v_add_f32_e32 v170, v231, v170
	v_mfma_f32_32x32x16_bf16 v[48:63], v[128:131], v[80:83], v[48:63]
	v_add_f32_e32 v170, v232, v170
	v_add_f32_e32 v170, v233, v170
	v_add_f32_e32 v170, v234, v170
	v_add_f32_e32 v170, v235, v170
	v_mfma_f32_32x32x16_bf16 v[64:79], v[132:135], v[84:87], v[64:79]
	v_add_f32_e32 v170, v236, v170
	v_add_f32_e32 v170, v237, v170
	v_add_f32_e32 v170, v238, v170
	v_add_f32_e32 v170, v239, v170
	v_mfma_f32_32x32x16_bf16 v[48:63], v[10:13], v[84:87], v[48:63]
	v_add_f32_e32 v170, v240, v170
	v_add_f32_e32 v170, v241, v170
	v_add_f32_e32 v170, v242, v170
	v_add_f32_e32 v170, v243, v170
	v_cvt_pk_bf16_f32 v228, v228, v229
	v_cvt_pk_bf16_f32 v229, v230, v231
	v_cvt_pk_bf16_f32 v230, v232, v233
	v_cvt_pk_bf16_f32 v231, v234, v235
	v_cvt_pk_bf16_f32 v232, v236, v237
	v_cvt_pk_bf16_f32 v233, v238, v239
	v_cvt_pk_bf16_f32 v234, v240, v241
	v_cvt_pk_bf16_f32 v235, v242, v243
	v_mfma_f32_32x32x16_bf16 v[32:47], v[136:139], v[228:231], v[32:47]
	v_mfma_f32_32x32x16_bf16 v[16:31], v[128:131], v[228:231], v[16:31]
	v_mfma_f32_32x32x16_bf16 v[32:47], v[132:135], v[232:235], v[32:47]
	v_mfma_f32_32x32x16_bf16 v[16:31], v[10:13], v[232:235], v[16:31]
	s_waitcnt lgkmcnt(0)
; #define LAS __attribute__((address_space(3)))
; DI f32x16 mfma32(bf16x8 a, bf16x8 b, f32x16 c) { return __builtin_amdgcn_mfma_f32_32x32x16_bf16(a, b, c, 0, 0, 0); }
; DI float ex2(float x) { return __builtin_amdgcn_exp2f(x); }
; template <int MODE>
; DI void sub_tile(const bf16x8 (&kf)[4], const bf16x8 (&vf)[2][2], const bf16x8 (&qf)[4], f32x16& o0, f32x16& o1, float& l, bool diag, float offs, float fm, const LAS float* fsp, int r, int h) {
;     ...
;     if (MODE == 2) {
; #pragma unroll
;         for (int i = 0; i < 16; ++i) x[i] = offs;
; #pragma unroll
;         for (int sp = 0; sp < 4; ++sp) x = mfma32(kf[sp], qf[sp], x);
; #pragma unroll
;         for (int i = 0; i < 16; ++i) p[i] = ex2(x[i]);
; template <int MODE>
; DI void attn_wg2_item(const bf16_t* Qm, const bf16_t* Km, const bf16_t* Vtm, const float* Fb, const float* KMPb, const bf16_t* G, bf16_t* Y, int bh, int qb2, int halfq, int mixer, float Mb, LAS unsigned char* lds, int tid, int wave, int lane) {
;     ...
;                 bf16x8 kf[4], vf[2][2];
; #pragma unroll
;                 for (int sp = 0; sp < 4; ++sp) kf[sp] = *(LAS bf16x8*)(lb + kra + kk * 32 * 144 + sp * 32);
; #pragma unroll
;                 for (int dd = 0; dd < 2; ++dd)
; #pragma unroll
;                     for (int s = 0; s < 2; ++s) vf[dd][s] = *(LAS bf16x8*)(lb + vra + dd * 32 * 144 + kk * 64 + s * 32);
;                 float offA = mb2, offB = mb2;
;                 if (MODE == 2) { offA = ((nb == qblkA) || ((selA >> nb) & 1u)) ? mb2 : NEGI; offB = ((nb == qblkB) || ((selB >> nb) & 1u)) ? mb2 : NEGI; }
;                 const LAS float* fsp = (const LAS float*)(lb + AW_F) + kk * 32;
;                 if (actA) sub_tile<MODE>(kf, vf, qfA, oA0, oA1, lA, tau == qtA, offA, fmA, fsp, r, h);
;                 if (actB) sub_tile<MODE>(kf, vf, qfB, oB0, oB1, lB, tau == qtB, offB, fmB, fsp, r, h);
	v_mfma_f32_32x32x16_bf16 v[80:95], v[152:155], v[96:99], v[196:211]
	v_mfma_f32_32x32x16_bf16 v[80:95], v[148:151], v[100:103], v[80:95]
	v_mfma_f32_32x32x16_bf16 v[80:95], v[144:147], v[104:107], v[80:95]
	v_mfma_f32_32x32x16_bf16 v[80:95], v[140:143], v[108:111], v[80:95]
	ds_read_b128 v[136:139], v0 offset:9216
	ds_read_b128 v[132:135], v0 offset:9248
	ds_read_b128 v[128:131], v0 offset:13824
	ds_read_b128 v[10:13], v0 offset:13856
	v_mfma_f32_32x32x16_bf16 v[228:243], v[152:155], v[112:115], v[212:227]
	v_mfma_f32_32x32x16_bf16 v[228:243], v[148:151], v[116:119], v[228:243]
	v_mfma_f32_32x32x16_bf16 v[228:243], v[144:147], v[120:123], v[228:243]
	v_mfma_f32_32x32x16_bf16 v[228:243], v[140:143], v[124:127], v[228:243]
	s_nop 7
	v_exp_f32_e32 v80, v80
	v_exp_f32_e32 v81, v81
	v_exp_f32_e32 v82, v82
	v_exp_f32_e32 v83, v83
	v_exp_f32_e32 v84, v84
	v_exp_f32_e32 v85, v85
	v_exp_f32_e32 v86, v86
	v_exp_f32_e32 v87, v87
	v_exp_f32_e32 v88, v88
	v_exp_f32_e32 v89, v89
	v_exp_f32_e32 v90, v90
	v_exp_f32_e32 v91, v91
	v_exp_f32_e32 v92, v92
	v_exp_f32_e32 v93, v93
	v_exp_f32_e32 v94, v94
	v_exp_f32_e32 v95, v95
	v_exp_f32_e32 v228, v228
	v_add_f32_e32 v186, v80, v186
	v_exp_f32_e32 v229, v229
	v_add_f32_e32 v186, v81, v186
	v_exp_f32_e32 v230, v230
	v_add_f32_e32 v186, v82, v186
	v_exp_f32_e32 v231, v231
	v_add_f32_e32 v186, v83, v186
	v_exp_f32_e32 v232, v232
	v_add_f32_e32 v186, v84, v186
	v_exp_f32_e32 v233, v233
	v_add_f32_e32 v186, v85, v186
	v_exp_f32_e32 v234, v234
	v_add_f32_e32 v186, v86, v186
	v_exp_f32_e32 v235, v235
	v_add_f32_e32 v186, v87, v186
	v_exp_f32_e32 v236, v236
	v_add_f32_e32 v186, v88, v186
	v_exp_f32_e32 v237, v237
	v_add_f32_e32 v186, v89, v186
	v_exp_f32_e32 v238, v238
	v_add_f32_e32 v186, v90, v186
	v_exp_f32_e32 v239, v239
	v_add_f32_e32 v186, v91, v186
	v_exp_f32_e32 v240, v240
	v_add_f32_e32 v186, v92, v186
	v_exp_f32_e32 v241, v241
	v_add_f32_e32 v186, v93, v186
	v_exp_f32_e32 v242, v242
	v_add_f32_e32 v186, v94, v186
	v_exp_f32_e32 v243, v243
	v_add_f32_e32 v186, v95, v186
	s_waitcnt lgkmcnt(0)
	v_cvt_pk_bf16_f32 v80, v80, v81
	v_cvt_pk_bf16_f32 v81, v82, v83
	v_cvt_pk_bf16_f32 v82, v84, v85
	v_cvt_pk_bf16_f32 v83, v86, v87
	v_cvt_pk_bf16_f32 v84, v88, v89
	v_cvt_pk_bf16_f32 v85, v90, v91
	v_cvt_pk_bf16_f32 v86, v92, v93
	v_cvt_pk_bf16_f32 v87, v94, v95
	v_mfma_f32_32x32x16_bf16 v[64:79], v[136:139], v[80:83], v[64:79]
	v_add_f32_e32 v170, v228, v170
	v_add_f32_e32 v170, v229, v170
	v_add_f32_e32 v170, v230, v170
	v_add_f32_e32 v170, v231, v170
	v_mfma_f32_32x32x16_bf16 v[48:63], v[128:131], v[80:83], v[48:63]
	v_add_f32_e32 v170, v232, v170
	v_add_f32_e32 v170, v233, v170
	v_add_f32_e32 v170, v234, v170
	v_add_f32_e32 v170, v235, v170
	v_mfma_f32_32x32x16_bf16 v[64:79], v[132:135], v[84:87], v[64:79]
	v_add_f32_e32 v170, v236, v170
	v_add_f32_e32 v170, v237, v170
	v_add_f32_e32 v170, v238, v170
	v_add_f32_e32 v170, v239, v170
	v_mfma_f32_32x32x16_bf16 v[48:63], v[10:13], v[84:87], v[48:63]
	v_add_f32_e32 v170, v240, v170
	v_add_f32_e32 v170, v241, v170
	v_add_f32_e32 v170, v242, v170
	v_add_f32_e32 v170, v243, v170
	v_cvt_pk_bf16_f32 v228, v228, v229
	v_cvt_pk_bf16_f32 v229, v230, v231
	v_cvt_pk_bf16_f32 v230, v232, v233
	v_cvt_pk_bf16_f32 v231, v234, v235
	v_cvt_pk_bf16_f32 v232, v236, v237
	v_cvt_pk_bf16_f32 v233, v238, v239
	v_cvt_pk_bf16_f32 v234, v240, v241
	v_cvt_pk_bf16_f32 v235, v242, v243
	v_mfma_f32_32x32x16_bf16 v[32:47], v[136:139], v[228:231], v[32:47]
	v_mfma_f32_32x32x16_bf16 v[16:31], v[128:131], v[228:231], v[16:31]
	v_mfma_f32_32x32x16_bf16 v[32:47], v[132:135], v[232:235], v[32:47]
	v_mfma_f32_32x32x16_bf16 v[16:31], v[10:13], v[232:235], v[16:31]
	s_branch .LBB0_413
